# v47 + P1 norm loop: cache-line-touching dummy load of the row after next (prefetch depth 2) and pre-store wait vmcnt(0)->vmcnt(1)
# speedup vs baseline: 1.0019x; 1.0019x over previous
; __device__ __forceinline__ unsigned pk2(float lo, float hi) { f32x2 v = {lo, hi}; nbf2 r = __builtin_convertvector(v, nbf2); return __builtin_bit_cast(unsigned, r); }
; __device__ __forceinline__ void norm_mod_phase(const float* xlat, const float* xctx, const float* nw, const float* mod, bf16_t* H) {
;     const int lane = threadIdx.x & 63, gw = blockIdx.x * 8 + (threadIdx.x >> 6), NGW = gridDim.x * 8;
;     f32x4 w4[4];
; #pragma unroll
;     for (int j = 0; j < 4; ++j) w4[j] = ((const f32x4*)nw)[lane + 64 * j];
;     const int per = NLAT / NGW;
;     const int nrows = per + ((gw < NCTX && NGW >= NCTX) ? 1 : 0);
;     if (NLAT % NGW != 0 || NGW < NCTX) {
;         for (int r = gw; r < MTOT; r += NGW) {
;             const float* xr = norm_src(xlat, xctx, r); const float* mp = mod + (r < NLAT ? (r >> 12) : 4) * 3072;
;             f32x4 v[4]; float s = 0.f;
; #pragma unroll
;             for (int j = 0; j < 4; ++j) { v[j] = ((const f32x4*)xr)[lane + 64 * j]; s += (v[j].x * v[j].x + v[j].y * v[j].y) + (v[j].z * v[j].z + v[j].w * v[j].w); }
;             const float rstd = 1.0f / sqrtf(wave_sum(s) * (1.0f / D) + 1e-6f);
;             unsigned long long* o8 = (unsigned long long*)(H + (size_t)r * D) + lane;
; #pragma unroll
;             for (int j = 0; j < 4; ++j) { const f32x4 sh = ((const f32x4*)mp)[lane + 64 * j], sc = ((const f32x4*)(mp + 1024))[lane + 64 * j];
;                 const f32x4 y = v[j] * rstd * w4[j] * (sc + 1.0f) + sh; o8[64 * j] = (unsigned long long)pk2(y.x, y.y) | ((unsigned long long)pk2(y.z, y.w) << 32); }
;         }
;         return;
;     }
;     const int r0 = gw * per;
;     f32x4 g4[4], sh4[4];
;     { const float* mp = mod + (r0 >> 12) * 3072;
; #pragma unroll
;       for (int j = 0; j < 4; ++j) { g4[j] = w4[j] * (((const f32x4*)(mp + 1024))[lane + 64 * j] + 1.0f); sh4[j] = ((const f32x4*)mp)[lane + 64 * j]; } }
;     f32x4 nx[4];
; #pragma unroll
;     for (int j = 0; j < 4; ++j) nx[j] = ((const f32x4*)(xlat + (size_t)r0 * D))[lane + 64 * j];
.LBB0_106:
	s_cmp_lt_i32 s68, 2
	s_cselect_b64 s[2:3], -1, 0
	s_add_u32 s16, s30, 0x2800000
	s_addc_u32 s17, s31, 0
	s_and_b64 s[4:5], s[2:3], s[0:1]
	s_andn2_b64 vcc, exec, s[4:5]
	s_cbranch_vccnz .LBB0_121
	v_and_b32_e32 v111, 63, v192
	v_lshlrev_b32_e32 v64, 4, v111
	s_waitcnt lgkmcnt(0)
	global_load_dwordx4 v[0:3], v64, s[44:45]
	global_load_dwordx4 v[4:7], v64, s[44:45] offset:1024
	global_load_dwordx4 v[8:11], v64, s[44:45] offset:2048
	global_load_dwordx4 v[12:15], v64, s[44:45] offset:3072
	s_lshl_b32 s6, s14, 3
	s_abs_i32 s0, s6
	v_cvt_f32_u32_e32 v16, s0
	s_sub_i32 s1, 0, s0
	s_bfe_i32 s2, s14, 0x1001c
	v_lshrrev_b32_e32 v17, 6, v192
	v_rcp_iflag_f32_e32 v16, v16
	v_or_b32_e32 v110, 64, v111
	v_or_b32_e32 v109, 0x80, v111
	v_or_b32_e32 v108, 0xc0, v111
	v_mul_f32_e32 v16, 0x4f7ffffe, v16
	v_cvt_u32_f32_e32 v16, v16
	v_lshl_add_u32 v66, s12, 3, v17
	v_readfirstlane_b32 s3, v16
	s_mul_i32 s1, s1, s3
	s_mul_hi_u32 s1, s3, s1
	s_add_i32 s3, s3, s1
	s_lshr_b32 s1, s3, 18
	s_mul_i32 s3, s1, s0
	s_sub_i32 s3, 0x4000, s3
	s_add_i32 s7, s1, 1
	s_sub_i32 s8, s3, s0
	s_cmp_ge_u32 s3, s0
	s_cselect_b32 s1, s7, s1
	s_cselect_b32 s3, s8, s3
	s_add_i32 s7, s1, 1
	s_cmp_ge_u32 s3, s0
	s_cselect_b32 s0, s7, s1
	s_xor_b32 s3, s0, s2
	s_sub_i32 s7, s3, s2
	s_mul_i32 s0, s7, s6
	s_cmpk_eq_i32 s0, 0x4000
	s_cselect_b64 s[0:1], -1, 0
	s_cmpk_gt_i32 s6, 0x3ff
	s_cselect_b64 s[8:9], -1, 0
	s_and_b64 s[8:9], s[8:9], s[0:1]
	s_mov_b64 s[0:1], -1
	s_and_b64 vcc, exec, s[8:9]
	s_cbranch_vccz .LBB0_116
	s_movk_i32 s0, 0x400
	s_cmpk_gt_i32 s6, 0x3ff
	v_cmp_gt_i32_e32 vcc, s0, v66
	s_cselect_b64 s[0:1], -1, 0
	v_mov_b32_e32 v16, s7
	s_and_b64 vcc, vcc, s[0:1]
	v_addc_co_u32_e64 v112, s[0:1], 0, v16, vcc
	v_cmp_lt_i32_e64 s[0:1], 0, v112
	s_and_saveexec_b64 s[8:9], s[0:1]
	s_cbranch_execz .LBB0_115
	v_mul_lo_u32 v68, s7, v66
	v_ashrrev_i32_e32 v16, 12, v68
	v_mul_i32_i24_e32 v16, 0xc00, v16
	v_ashrrev_i32_e32 v17, 31, v16
	v_mov_b32_e32 v65, 0
	v_lshl_add_u64 v[24:25], v[16:17], 2, s[30:31]
	s_mov_b64 s[0:1], 0x1000
	v_lshl_add_u64 v[16:17], v[24:25], 0, s[0:1]
	v_lshlrev_b32_e32 v88, 4, v108
	v_mov_b32_e32 v89, v65
	v_lshl_add_u64 v[18:19], v[16:17], 0, v[88:89]
	v_lshlrev_b32_e32 v84, 4, v109
	v_mov_b32_e32 v85, v65
	v_lshlrev_b32_e32 v80, 4, v110
	v_mov_b32_e32 v81, v65
	v_lshl_add_u64 v[20:21], v[16:17], 0, v[84:85]
	global_load_dwordx4 v[48:51], v[18:19], off
	global_load_dwordx4 v[52:55], v[20:21], off
	v_lshl_add_u64 v[18:19], v[16:17], 0, v[80:81]
	v_lshl_add_u64 v[16:17], v[16:17], 0, v[64:65]
	v_ashrrev_i32_e32 v69, 31, v68
	global_load_dwordx4 v[56:59], v[18:19], off
	global_load_dwordx4 v[60:63], v[16:17], off
	v_lshlrev_b64 v[16:17], 12, v[68:69]
	v_lshl_add_u64 v[16:17], s[36:37], 0, v[16:17]
	v_lshl_add_u64 v[26:27], v[16:17], 0, v[64:65]
	v_lshl_add_u64 v[70:71], v[24:25], 0, v[64:65]
	global_load_dwordx4 v[16:19], v[26:27], off offset:3072
	global_load_dwordx4 v[20:23], v[26:27], off offset:2048
	global_load_dwordx4 v[36:39], v[26:27], off offset:1024
	global_load_dwordx4 v[44:47], v[26:27], off
	global_load_dwordx4 v[40:43], v[70:71], off offset:3072
	s_nop 0
	global_load_dwordx4 v[24:27], v[70:71], off offset:2048
	global_load_dwordx4 v[28:31], v[70:71], off offset:1024
	global_load_dwordx4 v[32:35], v[70:71], off
	v_ashrrev_i32_e32 v67, 31, v66
	v_mbcnt_lo_u32_b32 v72, -1, 0
	v_lshlrev_b64 v[70:71], 12, v[66:67]
	v_mbcnt_hi_u32_b32 v67, -1, v72
	v_and_b32_e32 v72, 64, v67
	v_xor_b32_e32 v73, 1, v67
	v_add_u32_e32 v72, 64, v72
	v_cndmask_b32_e64 v106, 0, 1, vcc
	v_xor_b32_e32 v74, 2, v67
	v_cmp_lt_i32_e32 vcc, v73, v72
	v_xor_b32_e32 v75, 4, v67
	v_xor_b32_e32 v76, 8, v67
	v_cndmask_b32_e32 v73, v67, v73, vcc
	v_cmp_lt_i32_e32 vcc, v74, v72
	v_xor_b32_e32 v77, 16, v67
	s_add_u32 s0, s30, 0xc000
	v_cndmask_b32_e32 v74, v67, v74, vcc
	v_cmp_lt_i32_e32 vcc, v75, v72
	v_xor_b32_e32 v78, 32, v67
	s_addc_u32 s1, s31, 0
	v_cndmask_b32_e32 v75, v67, v75, vcc
	v_cmp_lt_i32_e32 vcc, v76, v72
	s_add_u32 s18, s30, 0xd000
	s_addc_u32 s19, s31, 0
	v_cndmask_b32_e32 v76, v67, v76, vcc
	v_cmp_lt_i32_e32 vcc, v77, v72
	s_sub_i32 s38, s2, s3
	v_add_u32_e32 v69, 0x4000, v66
	v_cndmask_b32_e32 v77, v67, v77, vcc
	v_cmp_lt_i32_e32 vcc, v78, v72
	s_mov_b32 s7, 1
	v_lshl_add_u64 v[70:71], s[40:41], 0, v[70:71]
	v_cndmask_b32_e32 v72, v67, v78, vcc
	v_lshlrev_b32_e32 v67, 2, v73
	v_lshlrev_b32_e32 v117, 2, v72
	v_lshlrev_b32_e32 v113, 2, v74
	v_lshlrev_b32_e32 v114, 2, v75
	v_lshlrev_b32_e32 v115, 2, v76
	v_lshlrev_b32_e32 v116, 2, v77
	v_lshl_add_u64 v[74:75], s[18:19], 0, v[64:65]
	v_lshl_add_u64 v[76:77], s[0:1], 0, v[64:65]
	v_lshl_add_u64 v[78:79], s[18:19], 0, v[80:81]
	v_lshl_add_u64 v[80:81], s[0:1], 0, v[80:81]
	v_lshl_add_u64 v[82:83], s[18:19], 0, v[84:85]
	v_lshl_add_u64 v[84:85], s[0:1], 0, v[84:85]
	v_lshl_add_u64 v[86:87], s[18:19], 0, v[88:89]
	v_lshl_add_u64 v[88:89], s[0:1], 0, v[88:89]
	v_sub_u32_e32 v118, s38, v106
	s_mov_b64 s[18:19], 0
	v_mov_b32_e32 v119, 0x358637bd
	s_mov_b32 s39, 0xf800000
	v_mov_b32_e32 v120, 0x260
	s_waitcnt vmcnt(11)
	v_pk_add_f32 v[48:49], v[48:49], 1.0 op_sel_hi:[1,0]
	v_pk_add_f32 v[50:51], v[50:51], 1.0 op_sel_hi:[1,0]
	s_waitcnt vmcnt(10)
	v_pk_add_f32 v[54:55], v[54:55], 1.0 op_sel_hi:[1,0]
	v_pk_add_f32 v[52:53], v[52:53], 1.0 op_sel_hi:[1,0]
	v_pk_mul_f32 v[98:99], v[12:13], v[48:49]
	s_waitcnt vmcnt(9)
	v_pk_add_f32 v[58:59], v[58:59], 1.0 op_sel_hi:[1,0]
	v_pk_add_f32 v[56:57], v[56:57], 1.0 op_sel_hi:[1,0]
	s_waitcnt vmcnt(8)
	v_pk_add_f32 v[62:63], v[62:63], 1.0 op_sel_hi:[1,0]
	v_pk_add_f32 v[60:61], v[60:61], 1.0 op_sel_hi:[1,0]
	v_lshlrev_b32_e32 v48, 3, v111
	v_mov_b32_e32 v49, v65
	v_pk_mul_f32 v[90:91], v[14:15], v[50:51]
	v_pk_mul_f32 v[92:93], v[10:11], v[54:55]
	v_pk_mul_f32 v[100:101], v[8:9], v[52:53]
	v_pk_mul_f32 v[94:95], v[6:7], v[58:59]
	v_pk_mul_f32 v[102:103], v[4:5], v[56:57]
	v_pk_mul_f32 v[96:97], v[2:3], v[62:63]
	v_pk_mul_f32 v[104:105], v[0:1], v[60:61]
	v_lshl_add_u64 v[72:73], s[16:17], 0, v[48:49]
	s_waitcnt vmcnt(7)
	v_mov_b64_e32 v[50:51], v[18:19]
	s_waitcnt vmcnt(6)
	v_mov_b64_e32 v[54:55], v[22:23]
	s_waitcnt vmcnt(5)
	v_mov_b64_e32 v[58:59], v[38:39]
	s_waitcnt vmcnt(4)
	v_mov_b64_e32 v[62:63], v[46:47]
	v_mov_b64_e32 v[48:49], v[16:17]
	v_mov_b64_e32 v[52:53], v[20:21]
	v_mov_b64_e32 v[56:57], v[36:37]
	v_mov_b64_e32 v[60:61], v[44:45]
	v_lshlrev_b32_e32 v134, 6, v111
	v_mov_b32_e32 v135, 0
	s_mov_b32 s99, 0
	s_branch .LBB0_111
; __device__ __forceinline__ unsigned pk2(float lo, float hi) { f32x2 v = {lo, hi}; nbf2 r = __builtin_convertvector(v, nbf2); return __builtin_bit_cast(unsigned, r); }
; __device__ __forceinline__ void norm_mod_phase(const float* xlat, const float* xctx, const float* nw, const float* mod, bf16_t* H) {
;     ...
;         float s = 0.f;
; #pragma unroll
;         for (int j = 0; j < 4; ++j) s += (v[j].x * v[j].x + v[j].y * v[j].y) + (v[j].z * v[j].z + v[j].w * v[j].w);
;         const float rstd = 1.0f / sqrtf(wave_sum(s) * (1.0f / D) + 1e-6f);
;         unsigned long long* o8 = (unsigned long long*)(H + (size_t)r * D) + lane;
; #pragma unroll
;         for (int j = 0; j < 4; ++j) {
;             const f32x4 y = v[j] * rstd * g4[j] + sh4[j];
;             o8[64 * j] = (unsigned long long)pk2(y.x, y.y) | ((unsigned long long)pk2(y.z, y.w) << 32);
;         }
;     }
.LBB0_110:
	v_pk_mul_f32 v[122:123], v[46:47], v[46:47]
	v_pk_mul_f32 v[124:125], v[44:45], v[44:45]
	v_mov_b32_e32 v127, v123
	v_mov_b32_e32 v126, v124
	v_pk_mov_b32 v[122:123], v[124:125], v[122:123] op_sel:[1,0]
	v_pk_mul_f32 v[124:125], v[38:39], v[38:39]
	v_pk_add_f32 v[122:123], v[122:123], v[126:127]
	v_pk_mul_f32 v[126:127], v[36:37], v[36:37]
	v_pk_add_f32 v[122:123], v[122:123], v[122:123] op_sel_hi:[0,1]
	v_mov_b32_e32 v128, v126
	v_mov_b32_e32 v129, v125
	v_pk_mov_b32 v[124:125], v[126:127], v[124:125] op_sel:[1,0]
	v_mul_f32_e32 v122, v20, v20
	v_pk_add_f32 v[124:125], v[124:125], v[128:129]
	v_pk_fma_f32 v[126:127], v[20:21], v[20:21], v[122:123] op_sel_hi:[1,1,0]
	v_mul_f32_e32 v122, v22, v22
	v_pk_add_f32 v[124:125], v[124:125], v[124:125] op_sel_hi:[0,1]
	v_pk_fma_f32 v[128:129], v[22:23], v[22:23], v[122:123] op_sel_hi:[1,1,0]
	v_mul_f32_e32 v126, v16, v16
	v_mul_f32_e32 v128, v17, v17
	v_mul_f32_e32 v124, v18, v18
	v_mul_f32_e32 v122, v19, v19
	v_pk_add_f32 v[126:127], v[126:127], v[128:129]
	v_pk_add_f32 v[122:123], v[124:125], v[122:123]
	v_add_u32_e32 v106, -1, v106
	v_pk_add_f32 v[122:123], v[126:127], v[122:123]
	v_cndmask_b32_e32 v106, v106, v69, vcc
	v_add_f32_e32 v107, v122, v123
	ds_bpermute_b32 v121, v67, v107
	s_add_i32 s7, s7, 1
	s_waitcnt lgkmcnt(0)
	v_add_f32_e32 v107, v107, v121
	ds_bpermute_b32 v121, v113, v107
	s_waitcnt lgkmcnt(0)
	v_add_f32_e32 v107, v107, v121
	ds_bpermute_b32 v121, v114, v107
	s_waitcnt lgkmcnt(0)
	v_add_f32_e32 v107, v107, v121
	ds_bpermute_b32 v121, v115, v107
	s_waitcnt lgkmcnt(0)
	v_add_f32_e32 v107, v107, v121
	ds_bpermute_b32 v121, v116, v107
	s_waitcnt lgkmcnt(0)
	v_add_f32_e32 v107, v107, v121
	ds_bpermute_b32 v121, v117, v107
	s_waitcnt lgkmcnt(0)
	v_add_f32_e32 v107, v107, v121
	v_fmamk_f32 v107, v107, 0x3a800000, v119
	v_mul_f32_e32 v121, 0x4f800000, v107
	v_cmp_gt_f32_e64 s[0:1], s39, v107
	s_nop 1
	v_cndmask_b32_e64 v107, v107, v121, s[0:1]
	v_sqrt_f32_e32 v121, v107
	s_nop 0
	v_add_u32_e32 v122, -1, v121
	v_add_u32_e32 v123, 1, v121
	v_fma_f32 v124, -v122, v121, v107
	v_fma_f32 v125, -v123, v121, v107
	v_cmp_ge_f32_e64 s[2:3], 0, v124
	s_nop 1
	v_cndmask_b32_e64 v121, v121, v122, s[2:3]
	v_cmp_lt_f32_e64 s[2:3], 0, v125
	s_nop 1
	v_cndmask_b32_e64 v121, v121, v123, s[2:3]
	v_mul_f32_e32 v122, 0x37800000, v121
	v_cndmask_b32_e64 v121, v121, v122, s[0:1]
	v_cmp_class_f32_e64 s[0:1], v107, v120
	s_nop 1
	v_cndmask_b32_e64 v107, v121, v107, s[0:1]
	v_div_scale_f32 v121, s[0:1], v107, v107, 1.0
	v_rcp_f32_e32 v122, v121
	v_div_scale_f32 v123, vcc, 1.0, v107, 1.0
	v_fma_f32 v124, -v121, v122, 1.0
	v_fmac_f32_e32 v122, v124, v122
	v_mul_f32_e32 v124, v123, v122
	v_fma_f32 v125, -v121, v124, v123
	v_fmac_f32_e32 v124, v125, v122
	v_fma_f32 v121, -v121, v124, v123
	v_div_fmas_f32 v121, v121, v122, v124
	v_div_fixup_f32 v122, v121, v107, 1.0
	v_ashrrev_i32_e32 v107, 31, v106
	v_pk_mul_f32 v[16:17], v[16:17], v[122:123] op_sel_hi:[1,0]
	v_pk_mul_f32 v[18:19], v[18:19], v[122:123] op_sel_hi:[1,0]
	v_lshlrev_b64 v[106:107], 11, v[106:107]
	v_pk_mul_f32 v[44:45], v[44:45], v[122:123] op_sel_hi:[1,0]
	v_pk_mul_f32 v[46:47], v[46:47], v[122:123] op_sel_hi:[1,0]
	v_pk_mul_f32 v[36:37], v[36:37], v[122:123] op_sel_hi:[1,0]
	v_pk_mul_f32 v[38:39], v[38:39], v[122:123] op_sel_hi:[1,0]
	v_pk_mul_f32 v[20:21], v[20:21], v[122:123] op_sel_hi:[1,0]
	v_pk_mul_f32 v[22:23], v[22:23], v[122:123] op_sel_hi:[1,0]
	s_waitcnt vmcnt(1)
	v_pk_fma_f32 v[18:19], v[90:91], v[18:19], v[42:43]
	v_pk_fma_f32 v[16:17], v[98:99], v[16:17], v[40:41]
	v_lshl_add_u64 v[106:107], v[72:73], 0, v[106:107]
	v_pk_fma_f32 v[46:47], v[96:97], v[46:47], v[34:35]
	v_pk_fma_f32 v[44:45], v[104:105], v[44:45], v[32:33]
	v_pk_fma_f32 v[38:39], v[94:95], v[38:39], v[30:31]
	v_pk_fma_f32 v[36:37], v[102:103], v[36:37], v[28:29]
	v_pk_fma_f32 v[22:23], v[92:93], v[22:23], v[26:27]
	v_pk_fma_f32 v[20:21], v[100:101], v[20:21], v[24:25]
	v_cvt_pk_bf16_f32 v16, v16, v17
	v_cvt_pk_bf16_f32 v17, v18, v19
	v_cvt_pk_bf16_f32 v44, v44, v45
	v_cvt_pk_bf16_f32 v45, v46, v47
	v_cvt_pk_bf16_f32 v36, v36, v37
	v_cvt_pk_bf16_f32 v37, v38, v39
	v_cvt_pk_bf16_f32 v20, v20, v21
	v_cvt_pk_bf16_f32 v21, v22, v23
	global_store_dwordx2 v[106:107], v[16:17], off offset:1536
	v_add_u32_e32 v16, s7, v118
	global_store_dwordx2 v[106:107], v[44:45], off
	global_store_dwordx2 v[106:107], v[36:37], off offset:512
	global_store_dwordx2 v[106:107], v[20:21], off offset:1024
	v_cmp_eq_u32_e32 vcc, 1, v16
	v_mov_b64_e32 v[16:17], v[48:49]
	v_mov_b64_e32 v[20:21], v[52:53]
	v_mov_b64_e32 v[36:37], v[56:57]
	v_mov_b64_e32 v[44:45], v[60:61]
	s_or_b64 s[18:19], vcc, s[18:19]
	v_mov_b64_e32 v[18:19], v[50:51]
	v_mov_b64_e32 v[22:23], v[54:55]
	v_mov_b64_e32 v[38:39], v[58:59]
	v_mov_b64_e32 v[46:47], v[62:63]
	s_andn2_b64 exec, exec, s[18:19]
	s_cbranch_execz .LBB0_115
; __device__ __forceinline__ void norm_mod_phase(const float* xlat, const float* xctx, const float* nw, const float* mod, bf16_t* H) {
;     ...
;     for (int k = 0; k < nrows; ++k) {
;         const bool isc = k == per;
;         const int r = isc ? NLAT + gw : r0 + k;
;         f32x4 v[4];
; #pragma unroll
;         for (int j = 0; j < 4; ++j) v[j] = nx[j];
;         if (k + 1 < nrows) { const float* xr = (k + 1 == per) ? xctx + (size_t)gw * D : xlat + (size_t)(r0 + k + 1) * D;
; #pragma unroll
;             for (int j = 0; j < 4; ++j) nx[j] = ((const f32x4*)xr)[lane + 64 * j]; }
;         if (isc) { const float* mp = mod + 4 * 3072;
; #pragma unroll
;             for (int j = 0; j < 4; ++j) { g4[j] = w4[j] * (((const f32x4*)(mp + 1024))[lane + 64 * j] + 1.0f); sh4[j] = ((const f32x4*)mp)[lane + 64 * j]; } }
.LBB0_111:
	s_add_i32 s2, s38, s7
	v_add_u32_e32 v106, s7, v68
	v_cmp_lt_i32_e32 vcc, s7, v112
	s_and_saveexec_b64 s[0:1], vcc
	s_cbranch_execz .LBB0_113
	v_ashrrev_i32_e32 v107, 31, v106
	s_cmp_eq_u32 s2, 0
	v_lshlrev_b64 v[48:49], 12, v[106:107]
	v_lshl_add_u64 v[48:49], s[36:37], 0, v[48:49]
	s_cselect_b64 vcc, -1, 0
	s_cmp_lt_u32 s7, 7
	s_cselect_b32 s98, 0x1000, 0
	v_cndmask_b32_e32 v49, v49, v71, vcc
	v_cndmask_b32_e32 v48, v48, v70, vcc
	v_lshl_add_u64 v[122:123], v[48:49], 0, v[64:65]
	v_lshl_add_u64 v[132:133], v[48:49], 0, v[134:135]
	v_lshl_add_u64 v[132:133], v[132:133], 0, s[98:99]
	global_load_dwordx4 v[60:63], v[122:123], off
	global_load_dwordx4 v[56:59], v[122:123], off offset:1024
	global_load_dwordx4 v[52:55], v[122:123], off offset:2048
	global_load_dwordx4 v[48:51], v[122:123], off offset:3072
	global_load_dword v130, v[132:133], off
.LBB0_113:
	s_or_b64 exec, exec, s[0:1]
	s_cmp_eq_u32 s2, 1
	s_cselect_b64 vcc, -1, 0
	s_cmp_lg_u32 s2, 1
	s_cbranch_scc1 .LBB0_110
	global_load_dwordx4 v[90:93], v[74:75], off
	global_load_dwordx4 v[94:97], v[78:79], off
	global_load_dwordx4 v[98:101], v[82:83], off
	global_load_dwordx4 v[102:105], v[86:87], off
	global_load_dwordx4 v[32:35], v[76:77], off
	global_load_dwordx4 v[28:31], v[80:81], off
	global_load_dwordx4 v[24:27], v[84:85], off
	global_load_dwordx4 v[40:43], v[88:89], off
	s_waitcnt vmcnt(7)
	v_pk_add_f32 v[92:93], v[92:93], 1.0 op_sel_hi:[1,0]
	v_pk_add_f32 v[90:91], v[90:91], 1.0 op_sel_hi:[1,0]
	s_waitcnt vmcnt(6)
	v_pk_add_f32 v[122:123], v[96:97], 1.0 op_sel_hi:[1,0]
	v_pk_add_f32 v[124:125], v[94:95], 1.0 op_sel_hi:[1,0]
	s_waitcnt vmcnt(5)
	v_pk_add_f32 v[100:101], v[100:101], 1.0 op_sel_hi:[1,0]
	v_pk_add_f32 v[98:99], v[98:99], 1.0 op_sel_hi:[1,0]
	s_waitcnt vmcnt(4)
	v_pk_add_f32 v[126:127], v[104:105], 1.0 op_sel_hi:[1,0]
	v_pk_add_f32 v[128:129], v[102:103], 1.0 op_sel_hi:[1,0]
	v_pk_mul_f32 v[96:97], v[2:3], v[92:93]
	v_pk_mul_f32 v[104:105], v[0:1], v[90:91]
	v_pk_mul_f32 v[94:95], v[6:7], v[122:123]
	v_pk_mul_f32 v[102:103], v[4:5], v[124:125]
	v_pk_mul_f32 v[92:93], v[10:11], v[100:101]
	v_pk_mul_f32 v[100:101], v[8:9], v[98:99]
	v_pk_mul_f32 v[90:91], v[14:15], v[126:127]
	v_pk_mul_f32 v[98:99], v[12:13], v[128:129]
	s_waitcnt vmcnt(0)
	s_branch .LBB0_110
